# gbar: leader releases XGEN before its own L1 invalidate; a128 gain load issued with row load
# baseline (speedup 1.0000x reference)
; __device__ __forceinline__ unsigned cvt_pk_bf16(float lo, float hi) { unsigned r; asm("v_cvt_pk_bf16_f32 %0, %1, %2" : "=v"(r) : "v"(lo), "v"(hi)); return r; }
; __device__ __forceinline__ int obid() { extern __shared__ __attribute__((aligned(16))) unsigned char shm_vb[]; return __builtin_amdgcn_readfirstlane(*(volatile LAS int*)((LAS unsigned char*)shm_vb + VB_OFF)); }
; __device__ __forceinline__ void phase_a128(const float* __restrict__ w, bf16_t* __restrict__ pk, const float* __restrict__ gain) {
;     ...
;   for (int i = obid() * 8 + (tid >> 6); i < 16 * 2048; i += nw) {
;     const int g = i >> 11, d = i & 2047;
;     const float4 v = *(const float4*)(w + (size_t)d * 8192 + g * 256 + lane * 4);
;     const float s = wave_sum(v.x - v.y + v.z - v.w) * 0.0625f * gain[d];
;     if (lane == 0) pk[(size_t)(2048 + g) * 2048 + d] = (bf16_t)(cvt_pk_bf16(s, 0.f) & 0xffffu);
.LBB0_42:
	v_ashrrev_i32_e32 v2, 11, v5
	v_and_b32_e32 v12, 0x7ff, v5
	v_lshlrev_b32_e32 v80, 15, v12
	v_lshlrev_b32_e32 v16, 8, v2
	v_lshl_add_u64 v[14:15], s[38:39], 0, v[80:81]
	v_ashrrev_i32_e32 v17, 31, v16
	v_lshl_add_u64 v[14:15], v[16:17], 2, v[14:15]
	v_mov_b32_e32 v1, v81
	v_lshl_add_u64 v[14:15], v[14:15], 0, v[0:1]
	global_load_dwordx4 v[14:17], v[14:15], off
	v_lshlrev_b32_e32 v80, 2, v12
	global_load_dword v13, v80, s[40:41]
	s_waitcnt vmcnt(0) lgkmcnt(0)
	v_sub_f32_e32 v1, v14, v15
	v_add_f32_e32 v1, v1, v16
	v_sub_f32_e32 v1, v1, v17
	ds_bpermute_b32 v3, v6, v1
	s_waitcnt lgkmcnt(0)
	v_add_f32_e32 v1, v1, v3
	ds_bpermute_b32 v3, v7, v1
	s_waitcnt lgkmcnt(0)
	v_add_f32_e32 v1, v1, v3
	ds_bpermute_b32 v3, v8, v1
	s_waitcnt lgkmcnt(0)
	v_add_f32_e32 v1, v1, v3
	ds_bpermute_b32 v3, v9, v1
	s_waitcnt lgkmcnt(0)
	v_add_f32_e32 v1, v1, v3
	ds_bpermute_b32 v3, v10, v1
	s_waitcnt lgkmcnt(0)
	v_add_f32_e32 v1, v1, v3
	ds_bpermute_b32 v3, v11, v1
	s_and_saveexec_b64 s[44:45], s[2:3]
	s_cbranch_execz .LBB0_41
	v_lshlrev_b32_e32 v80, 2, v12
	v_lshl_add_u64 v[14:15], s[40:41], 0, v[80:81]
	s_nop 0
	s_waitcnt lgkmcnt(0)
	v_add_f32_e32 v1, v1, v3
	v_ashrrev_i32_e32 v3, 31, v2
	v_lshlrev_b64 v[2:3], 12, v[2:3]
	v_lshlrev_b32_e32 v80, 1, v12
	v_lshl_add_u64 v[2:3], s[8:9], 0, v[2:3]
	v_lshl_add_u64 v[2:3], v[2:3], 0, v[80:81]
	v_mul_f32_e32 v1, 0x3d800000, v1
	v_add_co_u32_e32 v2, vcc, 0x800000, v2
	s_waitcnt vmcnt(0)
	v_mul_f32_e32 v1, v1, v13
	v_addc_co_u32_e32 v3, vcc, 0, v3, vcc
	v_cvt_pk_bf16_f32 v1, v1, v81
	global_store_short v[2:3], v1, off
	s_branch .LBB0_41

; __device__ __forceinline__ unsigned xb_add(unsigned* p, unsigned v) { return __hip_atomic_fetch_add(p, v, __ATOMIC_RELAXED, __HIP_MEMORY_SCOPE_AGENT); }
; __device__ __forceinline__ void gbar(unsigned* bar, unsigned n, volatile LAS unsigned* st) {
;     ...
;       __builtin_amdgcn_fence(__ATOMIC_ACQUIRE, "agent");
;       xb_add(&bar[XB_XGEN(x)], 1u);
;       asm volatile("s_waitcnt vmcnt(0)" ::: "memory");
.LBB0_81:
	s_or_b64 exec, exec, s[36:37]
	v_lshlrev_b64 v[0:1], 2, v[80:81]
	v_lshl_add_u64 v[0:1], s[4:5], 0, v[0:1]
	global_atomic_add v[0:1], v230, off
	buffer_inv sc1
	s_waitcnt vmcnt(0)

; __device__ __forceinline__ unsigned xb_add(unsigned* p, unsigned v) { return __hip_atomic_fetch_add(p, v, __ATOMIC_RELAXED, __HIP_MEMORY_SCOPE_AGENT); }
; __device__ __forceinline__ void gbar(unsigned* bar, unsigned n, volatile LAS unsigned* st) {
;     ...
;       __builtin_amdgcn_fence(__ATOMIC_ACQUIRE, "agent");
;       xb_add(&bar[XB_XGEN(x)], 1u);
;       asm volatile("s_waitcnt vmcnt(0)" ::: "memory");
.LBB0_215:
	s_or_b64 exec, exec, s[36:37]
	v_add_u32_e32 v80, 0x840, v0
	v_lshlrev_b64 v[0:1], 2, v[80:81]
	v_lshl_add_u64 v[0:1], s[4:5], 0, v[0:1]
	global_atomic_add v[0:1], v230, off
	buffer_inv sc1
	s_waitcnt vmcnt(0)

; __device__ __forceinline__ unsigned xb_add(unsigned* p, unsigned v) { return __hip_atomic_fetch_add(p, v, __ATOMIC_RELAXED, __HIP_MEMORY_SCOPE_AGENT); }
; __device__ __forceinline__ void gbar(unsigned* bar, unsigned n, volatile LAS unsigned* st) {
;     ...
;       __builtin_amdgcn_fence(__ATOMIC_ACQUIRE, "agent");
;       xb_add(&bar[XB_XGEN(x)], 1u);
;       asm volatile("s_waitcnt vmcnt(0)" ::: "memory");
.LBB0_317:
	s_or_b64 exec, exec, s[38:39]
	v_lshlrev_b64 v[0:1], 2, v[80:81]
	v_lshl_add_u64 v[0:1], s[4:5], 0, v[0:1]
	global_atomic_add v[0:1], v230, off
	buffer_inv sc1
	s_waitcnt vmcnt(0)

; __device__ __forceinline__ unsigned xb_add(unsigned* p, unsigned v) { return __hip_atomic_fetch_add(p, v, __ATOMIC_RELAXED, __HIP_MEMORY_SCOPE_AGENT); }
; __device__ __forceinline__ void gbar(unsigned* bar, unsigned n, volatile LAS unsigned* st) {
;     ...
;       __builtin_amdgcn_fence(__ATOMIC_ACQUIRE, "agent");
;       xb_add(&bar[XB_XGEN(x)], 1u);
;       asm volatile("s_waitcnt vmcnt(0)" ::: "memory");
.LBB0_535:
	s_or_b64 exec, exec, s[8:9]
	v_lshlrev_b64 v[0:1], 2, v[80:81]
	v_lshl_add_u64 v[0:1], s[4:5], 0, v[0:1]
	global_atomic_add v[0:1], v230, off
	buffer_inv sc1
	s_waitcnt vmcnt(0)
